# half of the accumulator clearing at each unit top done by four 32x32 MFMAs of zero operands (matrix pipe idle there), rest by v_mov
# speedup vs baseline: 1.0003x; 1.0003x over previous
;     __device__ bool next(int i, pg8::Unit& u) const { if (c < rem) return false; const int idx = (c - rem) + i * stride; if (idx >= nwg) return false; u.pm = idx / nN; u.pn = idx % nN; return true; }
; template <class Epi, class Sched, bool ALIGN_EPI = false, bool SP2 = false>
; __device__ __forceinline__ void gemm_phase(PG8_LAS unsigned char* lds, const Gemm g, const Sched& S, const Epi& E, const int w0) {
;     ...
;         const bool has_next = S.next(ui + 1, nxt);
;         const char* nA = has_next ? (const char*)g.A + (size_t)nxt.pm * tstep : cA; const char* nB = has_next ? (const char*)g.Bt + (size_t)nxt.pn * tstep : cB;
;     ...
; #pragma unroll
;         for (int a = 0; a < 2; ++a)
; #pragma unroll
;             for (int b = 0; b < 2; ++b)
; #pragma unroll
;                 for (int m = 0; m < 4; ++m)
; #pragma unroll
;                     for (int n = 0; n < 2; ++n) acc[a][b][m][n] = (f32x4){0.f, 0.f, 0.f, 0.f};
.LBB0_248:
	s_ashr_i32 s9, s8, 31
	s_lshl_b64 s[12:13], s[8:9], 17
	s_add_u32 s12, s47, s12
	s_addc_u32 s13, s50, s13
	s_and_b64 s[16:17], s[14:15], exec
	s_cselect_b32 s9, s13, s27
	s_cselect_b32 s83, s12, s26
	s_ashr_i32 s11, s10, 31
	s_lshl_b64 s[16:17], s[10:11], 17
	s_add_u32 s16, s52, s16
	s_addc_u32 s17, s53, s17
	s_and_b64 s[28:29], s[14:15], exec
	s_cselect_b32 s11, s17, s19
	s_cselect_b32 s84, s16, s18
	s_mov_b64 s[34:35], 0
	s_mov_b64 s[28:29], -1
	s_mov_b64 s[30:31], 0
	v_mov_b32_e32 v0, 0
	v_mov_b32_e32 v1, v0
	v_mov_b32_e32 v2, v0
	v_mov_b32_e32 v3, v0
	v_mov_b32_e32 v4, v0
	v_mov_b32_e32 v5, v0
	v_mov_b32_e32 v6, v0
	v_mov_b32_e32 v7, v0
	v_mfma_f32_32x32x16_bf16 v[16:31], v[0:3], v[0:3], 0
	v_mov_b32_e32 v8, v0
	v_mov_b32_e32 v9, v0
	v_mov_b32_e32 v10, v0
	v_mov_b32_e32 v11, v0
	v_mov_b32_e32 v12, v0
	v_mov_b32_e32 v13, v0
	v_mov_b32_e32 v14, v0
	v_mov_b32_e32 v15, v0
	v_mov_b32_e32 v80, v0
	v_mov_b32_e32 v81, v0
	v_mov_b32_e32 v82, v0
	v_mov_b32_e32 v83, v0
	v_mov_b32_e32 v84, v0
	v_mov_b32_e32 v85, v0
	v_mfma_f32_32x32x16_bf16 v[32:47], v[0:3], v[0:3], 0
	v_mov_b32_e32 v86, v0
	v_mov_b32_e32 v87, v0
	v_mov_b32_e32 v88, v0
	v_mov_b32_e32 v89, v0
	v_mov_b32_e32 v90, v0
	v_mov_b32_e32 v91, v0
	v_mov_b32_e32 v92, v0
	v_mov_b32_e32 v93, v0
	v_mov_b32_e32 v94, v0
	v_mov_b32_e32 v95, v0
	v_mov_b32_e32 v96, v0
	v_mov_b32_e32 v97, v0
	v_mov_b32_e32 v98, v0
	v_mov_b32_e32 v99, v0
	v_mfma_f32_32x32x16_bf16 v[48:63], v[0:3], v[0:3], 0
	v_mov_b32_e32 v100, v0
	v_mov_b32_e32 v101, v0
	v_mov_b32_e32 v102, v0
	v_mov_b32_e32 v103, v0
	v_mov_b32_e32 v104, v0
	v_mov_b32_e32 v105, v0
	v_mov_b32_e32 v106, v0
	v_mov_b32_e32 v107, v0
	v_mov_b32_e32 v108, v0
	v_mov_b32_e32 v109, v0
	v_mov_b32_e32 v110, v0
	v_mov_b32_e32 v111, v0
	v_mov_b32_e32 v112, v0
	v_mov_b32_e32 v113, v0
	v_mfma_f32_32x32x16_bf16 v[64:79], v[0:3], v[0:3], 0
	v_mov_b32_e32 v114, v0
	v_mov_b32_e32 v115, v0
	v_mov_b32_e32 v116, v0
	v_mov_b32_e32 v117, v0
	v_mov_b32_e32 v118, v0
	v_mov_b32_e32 v119, v0
	v_mov_b32_e32 v120, v0
	v_mov_b32_e32 v121, v0
	v_mov_b32_e32 v122, v0
	v_mov_b32_e32 v123, v0
	v_mov_b32_e32 v124, v0
	v_mov_b32_e32 v125, v0
	v_mov_b32_e32 v126, v0
	v_mov_b32_e32 v127, v0

;     __device__ bool next(int i, pg8::Unit& u) const { if (c < rem) return false; const int idx = (c - rem) + i * stride; if (idx >= nwg) return false; u.pm = idx / nN; u.pn = idx % nN; return true; }
; template <class Epi, class Sched, bool ALIGN_EPI = false, bool SP2 = false>
; __device__ __forceinline__ void gemm_phase(PG8_LAS unsigned char* lds, const Gemm g, const Sched& S, const Epi& E, const int w0) {
;     ...
;         const bool has_next = S.next(ui + 1, nxt);
;         const char* nA = has_next ? (const char*)g.A + (size_t)nxt.pm * tstep : cA; const char* nB = has_next ? (const char*)g.Bt + (size_t)nxt.pn * tstep : cB;
;     ...
; #pragma unroll
;         for (int a = 0; a < 2; ++a)
; #pragma unroll
;             for (int b = 0; b < 2; ++b)
; #pragma unroll
;                 for (int m = 0; m < 4; ++m)
; #pragma unroll
;                     for (int n = 0; n < 2; ++n) acc[a][b][m][n] = (f32x4){0.f, 0.f, 0.f, 0.f};
.LBB0_276:
	s_ashr_i32 s73, s72, 31
	s_lshl_b64 s[12:13], s[72:73], 19
	s_add_u32 s74, s47, s12
	s_addc_u32 s75, s50, s13
	s_and_b64 s[12:13], s[14:15], exec
	s_cselect_b32 s5, s75, s9
	s_cselect_b32 s7, s74, s8
	s_ashr_i32 s71, s70, 31
	s_lshl_b64 s[12:13], s[70:71], 19
	s_add_u32 s76, s52, s12
	s_addc_u32 s77, s53, s13
	s_and_b64 s[12:13], s[14:15], exec
	s_cselect_b32 s16, s77, s11
	s_cselect_b32 s17, s76, s10
	s_add_u32 s8, s8, 0x40080
	s_addc_u32 s9, s9, 0
	s_add_u32 s18, s10, 0x100
	s_addc_u32 s19, s11, 0
	s_mov_b32 s20, -2
	v_mov_b32_e32 v0, 0
	v_mov_b32_e32 v1, v0
	v_mov_b32_e32 v2, v0
	v_mov_b32_e32 v3, v0
	v_mov_b32_e32 v4, v0
	v_mov_b32_e32 v5, v0
	v_mov_b32_e32 v6, v0
	v_mov_b32_e32 v7, v0
	v_mfma_f32_32x32x16_bf16 v[16:31], v[0:3], v[0:3], 0
	v_mov_b32_e32 v8, v0
	v_mov_b32_e32 v9, v0
	v_mov_b32_e32 v10, v0
	v_mov_b32_e32 v11, v0
	v_mov_b32_e32 v12, v0
	v_mov_b32_e32 v13, v0
	v_mov_b32_e32 v14, v0
	v_mov_b32_e32 v15, v0
	v_mov_b32_e32 v80, v0
	v_mov_b32_e32 v81, v0
	v_mov_b32_e32 v82, v0
	v_mov_b32_e32 v83, v0
	v_mov_b32_e32 v84, v0
	v_mov_b32_e32 v85, v0
	v_mfma_f32_32x32x16_bf16 v[32:47], v[0:3], v[0:3], 0
	v_mov_b32_e32 v86, v0
	v_mov_b32_e32 v87, v0
	v_mov_b32_e32 v88, v0
	v_mov_b32_e32 v89, v0
	v_mov_b32_e32 v90, v0
	v_mov_b32_e32 v91, v0
	v_mov_b32_e32 v92, v0
	v_mov_b32_e32 v93, v0
	v_mov_b32_e32 v94, v0
	v_mov_b32_e32 v95, v0
	v_mov_b32_e32 v112, v0
	v_mov_b32_e32 v113, v0
	v_mov_b32_e32 v114, v0
	v_mov_b32_e32 v115, v0
	v_mfma_f32_32x32x16_bf16 v[48:63], v[0:3], v[0:3], 0
	v_mov_b32_e32 v116, v0
	v_mov_b32_e32 v117, v0
	v_mov_b32_e32 v118, v0
	v_mov_b32_e32 v119, v0
	v_mov_b32_e32 v120, v0
	v_mov_b32_e32 v121, v0
	v_mov_b32_e32 v122, v0
	v_mov_b32_e32 v123, v0
	v_mov_b32_e32 v124, v0
	v_mov_b32_e32 v125, v0
	v_mov_b32_e32 v126, v0
	v_mov_b32_e32 v127, v0
	v_mov_b32_e32 v128, v0
	v_mov_b32_e32 v129, v0
	v_mfma_f32_32x32x16_bf16 v[64:79], v[0:3], v[0:3], 0
	v_mov_b32_e32 v130, v0
	v_mov_b32_e32 v131, v0
	v_mov_b32_e32 v132, v0
	v_mov_b32_e32 v133, v0
	v_mov_b32_e32 v134, v0
	v_mov_b32_e32 v135, v0
	v_mov_b32_e32 v136, v0
	v_mov_b32_e32 v137, v0
	v_mov_b32_e32 v138, v0
	v_mov_b32_e32 v139, v0
	v_mov_b32_e32 v140, v0
	v_mov_b32_e32 v141, v0
	v_mov_b32_e32 v142, v0
	v_mov_b32_e32 v143, v0

;     __device__ bool next(int i, pg8::Unit& u) const { if (c < rem) return false; const int idx = (c - rem) + i * stride; if (idx >= nwg) return false; u.pm = idx / nN; u.pn = idx % nN; return true; }
; template <class Epi, class Sched, bool ALIGN_EPI = false, bool SP2 = false>
; __device__ __forceinline__ void gemm_phase(PG8_LAS unsigned char* lds, const Gemm g, const Sched& S, const Epi& E, const int w0) {
;     ...
;         const bool has_next = S.next(ui + 1, nxt);
;         const char* nA = has_next ? (const char*)g.A + (size_t)nxt.pm * tstep : cA; const char* nB = has_next ? (const char*)g.Bt + (size_t)nxt.pn * tstep : cB;
;     ...
; #pragma unroll
;         for (int a = 0; a < 2; ++a)
; #pragma unroll
;             for (int b = 0; b < 2; ++b)
; #pragma unroll
;                 for (int m = 0; m < 4; ++m)
; #pragma unroll
;                     for (int n = 0; n < 2; ++n) acc[a][b][m][n] = (f32x4){0.f, 0.f, 0.f, 0.f};
.LBB0_765:
	s_ashr_i32 s63, s62, 31
	s_lshl_b64 s[30:31], s[62:63], 19
	s_add_u32 s64, s2, s30
	s_addc_u32 s65, s3, s31
	s_and_b64 s[30:31], s[4:5], exec
	s_cselect_b32 s63, s65, s19
	s_cselect_b32 s77, s64, s18
	s_ashr_i32 s61, s60, 31
	s_lshl_b64 s[30:31], s[60:61], 19
	s_add_u32 s66, s7, s30
	s_addc_u32 s67, s20, s31
	s_and_b64 s[30:31], s[4:5], exec
	s_cselect_b32 s61, s67, s29
	s_cselect_b32 s78, s66, s28
	s_add_u32 s18, s18, 0x40080
	s_addc_u32 s19, s19, 0
	s_add_u32 s79, s28, 0x100
	s_addc_u32 s80, s29, 0
	s_mov_b32 s81, -2
	v_mov_b32_e32 v0, 0
	v_mov_b32_e32 v1, v0
	v_mov_b32_e32 v2, v0
	v_mov_b32_e32 v3, v0
	v_mov_b32_e32 v4, v0
	v_mov_b32_e32 v5, v0
	v_mov_b32_e32 v6, v0
	v_mov_b32_e32 v7, v0
	v_mfma_f32_32x32x16_bf16 v[16:31], v[0:3], v[0:3], 0
	v_mov_b32_e32 v8, v0
	v_mov_b32_e32 v9, v0
	v_mov_b32_e32 v10, v0
	v_mov_b32_e32 v11, v0
	v_mov_b32_e32 v12, v0
	v_mov_b32_e32 v13, v0
	v_mov_b32_e32 v14, v0
	v_mov_b32_e32 v15, v0
	v_mov_b32_e32 v80, v0
	v_mov_b32_e32 v81, v0
	v_mov_b32_e32 v82, v0
	v_mov_b32_e32 v83, v0
	v_mov_b32_e32 v84, v0
	v_mov_b32_e32 v85, v0
	v_mfma_f32_32x32x16_bf16 v[32:47], v[0:3], v[0:3], 0
	v_mov_b32_e32 v86, v0
	v_mov_b32_e32 v87, v0
	v_mov_b32_e32 v88, v0
	v_mov_b32_e32 v89, v0
	v_mov_b32_e32 v90, v0
	v_mov_b32_e32 v91, v0
	v_mov_b32_e32 v92, v0
	v_mov_b32_e32 v93, v0
	v_mov_b32_e32 v94, v0
	v_mov_b32_e32 v95, v0
	v_mov_b32_e32 v96, v0
	v_mov_b32_e32 v97, v0
	v_mov_b32_e32 v98, v0
	v_mov_b32_e32 v99, v0
	v_mfma_f32_32x32x16_bf16 v[48:63], v[0:3], v[0:3], 0
	v_mov_b32_e32 v100, v0
	v_mov_b32_e32 v101, v0
	v_mov_b32_e32 v102, v0
	v_mov_b32_e32 v103, v0
	v_mov_b32_e32 v104, v0
	v_mov_b32_e32 v105, v0
	v_mov_b32_e32 v106, v0
	v_mov_b32_e32 v107, v0
	v_mov_b32_e32 v108, v0
	v_mov_b32_e32 v109, v0
	v_mov_b32_e32 v110, v0
	v_mov_b32_e32 v111, v0
	v_mov_b32_e32 v112, v0
	v_mov_b32_e32 v113, v0
	v_mfma_f32_32x32x16_bf16 v[64:79], v[0:3], v[0:3], 0
	v_mov_b32_e32 v114, v0
	v_mov_b32_e32 v115, v0
	v_mov_b32_e32 v116, v0
	v_mov_b32_e32 v117, v0
	v_mov_b32_e32 v118, v0
	v_mov_b32_e32 v119, v0
	v_mov_b32_e32 v120, v0
	v_mov_b32_e32 v121, v0
	v_mov_b32_e32 v122, v0
	v_mov_b32_e32 v123, v0
	v_mov_b32_e32 v124, v0
	v_mov_b32_e32 v125, v0
	v_mov_b32_e32 v126, v0
	v_mov_b32_e32 v127, v0

;     __device__ bool next(int i, pg8::Unit& u) const { if (c < rem) return false; const int idx = (c - rem) + i * stride; if (idx >= nwg) return false; u.pm = idx / nN; u.pn = idx % nN; return true; }
; template <class Epi, class Sched, bool ALIGN_EPI = false, bool SP2 = false>
; __device__ __forceinline__ void gemm_phase(PG8_LAS unsigned char* lds, const Gemm g, const Sched& S, const Epi& E, const int w0) {
;     ...
;         const bool has_next = S.next(ui + 1, nxt);
;         const char* nA = has_next ? (const char*)g.A + (size_t)nxt.pm * tstep : cA; const char* nB = has_next ? (const char*)g.Bt + (size_t)nxt.pn * tstep : cB;
;     ...
; #pragma unroll
;         for (int a = 0; a < 2; ++a)
; #pragma unroll
;             for (int b = 0; b < 2; ++b)
; #pragma unroll
;                 for (int m = 0; m < 4; ++m)
; #pragma unroll
;                     for (int n = 0; n < 2; ++n) acc[a][b][m][n] = (f32x4){0.f, 0.f, 0.f, 0.f};
.LBB0_846:
	s_ashr_i32 s65, s64, 31
	s_lshl_b64 s[28:29], s[64:65], 19
	s_add_u32 s66, s2, s28
	s_addc_u32 s67, s3, s29
	s_and_b64 s[28:29], s[4:5], exec
	s_cselect_b32 s65, s67, s9
	s_cselect_b32 s72, s66, s8
	s_ashr_i32 s63, s62, 31
	s_lshl_b64 s[28:29], s[62:63], 19
	s_add_u32 s68, s6, s28
	s_addc_u32 s69, s7, s29
	s_and_b64 s[28:29], s[4:5], exec
	s_cselect_b32 s63, s69, s19
	s_cselect_b32 s73, s68, s18
	s_add_u32 s8, s8, 0x40080
	s_addc_u32 s9, s9, 0
	s_add_u32 s74, s18, 0x100
	s_addc_u32 s75, s19, 0
	s_mov_b32 s81, -2
	s_waitcnt lgkmcnt(0)
	v_mov_b32_e32 v0, 0
	v_mov_b32_e32 v1, v0
	v_mov_b32_e32 v2, v0
	v_mov_b32_e32 v3, v0
	v_mov_b32_e32 v4, v0
	v_mov_b32_e32 v5, v0
	v_mov_b32_e32 v6, v0
	v_mov_b32_e32 v7, v0
	v_mfma_f32_32x32x16_bf16 v[16:31], v[0:3], v[0:3], 0
	v_mov_b32_e32 v8, v0
	v_mov_b32_e32 v9, v0
	v_mov_b32_e32 v10, v0
	v_mov_b32_e32 v11, v0
	v_mov_b32_e32 v12, v0
	v_mov_b32_e32 v13, v0
	v_mov_b32_e32 v14, v0
	v_mov_b32_e32 v15, v0
	v_mov_b32_e32 v80, v0
	v_mov_b32_e32 v81, v0
	v_mov_b32_e32 v82, v0
	v_mov_b32_e32 v83, v0
	v_mov_b32_e32 v84, v0
	v_mov_b32_e32 v85, v0
	v_mfma_f32_32x32x16_bf16 v[32:47], v[0:3], v[0:3], 0
	v_mov_b32_e32 v86, v0
	v_mov_b32_e32 v87, v0
	v_mov_b32_e32 v88, v0
	v_mov_b32_e32 v89, v0
	v_mov_b32_e32 v90, v0
	v_mov_b32_e32 v91, v0
	v_mov_b32_e32 v92, v0
	v_mov_b32_e32 v93, v0
	v_mov_b32_e32 v94, v0
	v_mov_b32_e32 v95, v0
	v_mov_b32_e32 v96, v0
	v_mov_b32_e32 v97, v0
	v_mov_b32_e32 v98, v0
	v_mov_b32_e32 v99, v0
	v_mfma_f32_32x32x16_bf16 v[48:63], v[0:3], v[0:3], 0
	v_mov_b32_e32 v100, v0
	v_mov_b32_e32 v101, v0
	v_mov_b32_e32 v102, v0
	v_mov_b32_e32 v103, v0
	v_mov_b32_e32 v104, v0
	v_mov_b32_e32 v105, v0
	v_mov_b32_e32 v106, v0
	v_mov_b32_e32 v107, v0
	v_mov_b32_e32 v108, v0
	v_mov_b32_e32 v109, v0
	v_mov_b32_e32 v110, v0
	v_mov_b32_e32 v111, v0
	v_mov_b32_e32 v112, v0
	v_mov_b32_e32 v113, v0
	v_mfma_f32_32x32x16_bf16 v[64:79], v[0:3], v[0:3], 0
	v_mov_b32_e32 v114, v0
	v_mov_b32_e32 v115, v0
	v_mov_b32_e32 v116, v0
	v_mov_b32_e32 v117, v0
	v_mov_b32_e32 v118, v0
	v_mov_b32_e32 v119, v0
	v_mov_b32_e32 v136, v0
	v_mov_b32_e32 v137, v0
	v_mov_b32_e32 v138, v0
	v_mov_b32_e32 v139, v0
	v_mov_b32_e32 v148, v0
	v_mov_b32_e32 v149, v0
	v_mov_b32_e32 v150, v0
	v_mov_b32_e32 v151, v0
